# RMS-norm row sums by DPP all-reduce instead of ds_bpermute chains (pre-norm, post-norm gate path, final norm)
# speedup vs baseline: 1.0302x; 1.0026x over previous
.LBB0_121:
	s_waitcnt vmcnt(3)
	v_mov_b32_e32 v34, v17
	s_waitcnt vmcnt(2)
	v_mov_b32_e32 v35, v13
	v_mov_b32_e32 v32, v16
	v_mov_b32_e32 v33, v12
	v_pk_mul_f32 v[34:35], v[34:35], v[34:35]
	s_mul_i32 s0, s16, 9
	v_pk_fma_f32 v[32:33], v[32:33], v[32:33], v[34:35]
	v_mov_b32_e32 v34, v18
	v_mov_b32_e32 v35, v14
	v_pk_fma_f32 v[32:33], v[34:35], v[34:35], v[32:33]
	v_mov_b32_e32 v34, v19
	v_mov_b32_e32 v35, v15
	v_pk_fma_f32 v[46:47], v[34:35], v[34:35], v[32:33]
	s_waitcnt vmcnt(1)
	v_mov_b32_e32 v34, v9
	s_waitcnt vmcnt(0)
	v_mov_b32_e32 v35, v5
	v_mov_b32_e32 v32, v8
	v_mov_b32_e32 v33, v4
	v_pk_mul_f32 v[34:35], v[34:35], v[34:35]
	v_add_u32_e32 v1, s0, v1
	v_pk_fma_f32 v[48:49], v[32:33], v[32:33], v[34:35]
	v_mul_lo_u32 v32, v1, s17
	v_ashrrev_i32_e32 v33, 31, v32
	v_mov_b32_e32 v50, v10
	v_mov_b32_e32 v51, v6
	v_lshl_add_u64 v[32:33], v[32:33], 2, s[12:13]
	s_mov_b64 s[0:1], 0x1000
	v_lshl_add_u64 v[70:71], v[32:33], 0, s[0:1]
	v_pk_fma_f32 v[48:49], v[50:51], v[50:51], v[48:49]
	v_mov_b32_e32 v50, v11
	v_mov_b32_e32 v51, v7
	v_mov_b32_e32 v29, v222
	v_mov_b32_e32 v31, v222
	v_mov_b32_e32 v37, v222
	v_mov_b32_e32 v82, v222
	v_mov_b32_e32 v83, v222
	v_mov_b32_e32 v84, v222
	v_lshl_add_u64 v[38:39], v[70:71], 0, v[2:3]
	v_pk_fma_f32 v[58:59], v[50:51], v[50:51], v[48:49]
	v_add_f32_e32 v1, v46, v47
	v_mov_b32_e32 v27, v3
	v_lshl_add_u64 v[78:79], v[32:33], 0, v[2:3]
	global_load_dwordx4 v[32:35], v[22:23], off
	s_nop 0
	global_load_dwordx4 v[38:41], v[38:39], off
	s_nop 0
	global_load_dwordx4 v[42:45], v[78:79], off
	v_lshl_add_u64 v[50:51], v[70:71], 0, v[26:27]
	v_add_f32_e32 v1, v1, v58
	v_lshlrev_b32_e32 v27, 2, v29
	v_add_f32_e32 v1, v1, v59
	v_bitop3_b32 v27, v27, s18, v229 bitop3:0x6c
	global_load_dwordx4 v[46:49], v[22:23], off offset:1024
	s_nop 0
	global_load_dwordx4 v[50:53], v[50:51], off
	s_nop 0
	global_load_dwordx4 v[54:57], v[78:79], off offset:1024
	v_mov_b32_e32 v29, v3
	v_lshl_add_u64 v[62:63], v[70:71], 0, v[28:29]
	global_load_dwordx4 v[58:61], v[22:23], off offset:2048
	s_nop 0
	global_load_dwordx4 v[62:65], v[62:63], off
	s_nop 0
	global_load_dwordx4 v[66:69], v[78:79], off offset:2048
	s_waitcnt lgkmcnt(0)
	v_lshlrev_b32_e32 v27, 2, v31
	v_mov_b32_e32 v31, v3
	v_lshl_add_u64 v[74:75], v[70:71], 0, v[30:31]
	global_load_dwordx4 v[70:73], v[22:23], off offset:3072
	s_nop 0
	global_load_dwordx4 v[74:77], v[74:75], off
	s_nop 0
	global_load_dwordx4 v[78:81], v[78:79], off offset:3072
	v_bitop3_b32 v27, v27, 64, v229 bitop3:0x6c
	s_mov_b32 s0, 0xfbc00000
	s_waitcnt lgkmcnt(0)
	v_lshlrev_b32_e32 v27, 2, v37
	v_bitop3_b32 v27, v27, 32, v229 bitop3:0x6c
	s_waitcnt lgkmcnt(0)
	v_lshlrev_b32_e32 v27, 2, v82
	v_bitop3_b32 v27, v27, 16, v229 bitop3:0x6c
	s_waitcnt lgkmcnt(0)
	v_lshlrev_b32_e32 v27, 2, v83
	v_bitop3_b32 v27, v27, 8, v229 bitop3:0x6c
	s_waitcnt lgkmcnt(0)
	v_lshlrev_b32_e32 v27, 2, v84
	v_bitop3_b32 v27, v27, 4, v229 bitop3:0x6c
	s_waitcnt lgkmcnt(0)
	s_nop 1
	v_add_f32_dpp v1, v1, v1 quad_perm:[1,0,3,2] row_mask:0xf bank_mask:0xf
	s_nop 1
	v_add_f32_dpp v1, v1, v1 quad_perm:[2,3,0,1] row_mask:0xf bank_mask:0xf
	s_nop 1
	v_add_f32_dpp v1, v1, v1 row_half_mirror row_mask:0xf bank_mask:0xf
	s_nop 1
	v_add_f32_dpp v1, v1, v1 row_mirror row_mask:0xf bank_mask:0xf
	s_nop 1
	v_add_f32_dpp v1, v1, v1 row_bcast:15 row_mask:0xa bank_mask:0xf
	s_nop 1
	v_add_f32_dpp v1, v1, v1 row_bcast:31 row_mask:0xc bank_mask:0xf
	s_nop 1
	v_readlane_b32 s98, v1, 63
	s_nop 1
	v_mov_b32_e32 v1, s98
	v_fmamk_f32 v1, v1, 0x3a800000, v223
	v_mul_f32_e32 v27, 0x4b800000, v1
	v_cmp_gt_f32_e32 vcc, s19, v1
	s_nop 1
	v_cndmask_b32_e32 v1, v1, v27, vcc
	v_rsq_f32_e32 v1, v1
	s_nop 0
	v_mul_f32_e32 v27, 0x45800000, v1
	v_cndmask_b32_e32 v82, v1, v27, vcc
	v_pk_mul_f32 v[16:17], v[16:17], v[82:83] op_sel_hi:[1,0]
	v_pk_mul_f32 v[18:19], v[18:19], v[82:83] op_sel_hi:[1,0]
	v_pk_mul_f32 v[12:13], v[12:13], v[82:83] op_sel_hi:[1,0]
	v_pk_mul_f32 v[14:15], v[14:15], v[82:83] op_sel_hi:[1,0]
	v_pk_mul_f32 v[8:9], v[8:9], v[82:83] op_sel_hi:[1,0]
	v_pk_mul_f32 v[10:11], v[10:11], v[82:83] op_sel_hi:[1,0]
	v_pk_mul_f32 v[4:5], v[4:5], v[82:83] op_sel_hi:[1,0]
	v_pk_mul_f32 v[6:7], v[6:7], v[82:83] op_sel_hi:[1,0]
	s_waitcnt vmcnt(11)
	v_pk_mul_f32 v[16:17], v[32:33], v[16:17]
	s_waitcnt vmcnt(10)
	v_pk_add_f32 v[32:33], v[38:39], 1.0 op_sel_hi:[1,0]
	v_pk_mul_f32 v[18:19], v[18:19], v[34:35]
	s_waitcnt vmcnt(9)
	v_pk_fma_f32 v[16:17], v[32:33], v[16:17], v[42:43]
	v_pk_add_f32 v[32:33], v[40:41], 1.0 op_sel_hi:[1,0]
	v_cvt_pk_bf16_f32 v16, v16, v17
	v_pk_fma_f32 v[18:19], v[32:33], v[18:19], v[44:45]
	s_waitcnt vmcnt(8)
	v_pk_mul_f32 v[12:13], v[12:13], v[46:47]
	v_cvt_pk_bf16_f32 v17, v18, v19
	s_waitcnt vmcnt(7)
	v_pk_add_f32 v[18:19], v[50:51], 1.0 op_sel_hi:[1,0]
	v_pk_mul_f32 v[14:15], v[14:15], v[48:49]
	s_waitcnt vmcnt(6)
	v_pk_fma_f32 v[12:13], v[18:19], v[12:13], v[54:55]
	v_pk_add_f32 v[18:19], v[52:53], 1.0 op_sel_hi:[1,0]
	v_cvt_pk_bf16_f32 v12, v12, v13
	v_pk_fma_f32 v[14:15], v[18:19], v[14:15], v[56:57]
	s_waitcnt vmcnt(5)
	v_pk_mul_f32 v[8:9], v[8:9], v[58:59]
	v_cvt_pk_bf16_f32 v13, v14, v15
	s_waitcnt vmcnt(4)
	v_pk_add_f32 v[14:15], v[62:63], 1.0 op_sel_hi:[1,0]
	v_pk_mul_f32 v[10:11], v[10:11], v[60:61]
	s_waitcnt vmcnt(3)
	v_pk_fma_f32 v[8:9], v[14:15], v[8:9], v[66:67]
	v_pk_add_f32 v[14:15], v[64:65], 1.0 op_sel_hi:[1,0]
	v_cvt_pk_bf16_f32 v8, v8, v9
	v_pk_fma_f32 v[10:11], v[14:15], v[10:11], v[68:69]
	s_waitcnt vmcnt(2)
	v_pk_mul_f32 v[4:5], v[4:5], v[70:71]
	v_cvt_pk_bf16_f32 v9, v10, v11
	s_waitcnt vmcnt(1)
	v_pk_add_f32 v[10:11], v[74:75], 1.0 op_sel_hi:[1,0]
	v_pk_mul_f32 v[6:7], v[6:7], v[72:73]
	s_waitcnt vmcnt(0)
	v_pk_fma_f32 v[4:5], v[10:11], v[4:5], v[78:79]
	v_add_co_u32_e32 v10, vcc, s0, v24
	s_mov_b32 s0, 0xfbc01000
	s_nop 0
	v_addc_co_u32_e32 v11, vcc, -1, v25, vcc
	global_store_dwordx2 v[10:11], v[16:17], off
	v_add_co_u32_e32 v10, vcc, s0, v24
	v_readlane_b32 s0, v252, 23
	s_nop 0
	v_addc_co_u32_e32 v11, vcc, -1, v25, vcc
	v_readlane_b32 s1, v252, 24
	v_add_u32_e32 v0, s0, v0
	s_mov_b32 s0, 0x87ff
	global_store_dwordx2 v[10:11], v[12:13], off offset:-3584
	global_store_dwordx2 v[10:11], v[8:9], off offset:-3072
	v_pk_add_f32 v[8:9], v[76:77], 1.0 op_sel_hi:[1,0]
	v_cmp_lt_i32_e32 vcc, s0, v0
	v_readlane_b32 s0, v252, 25
	v_pk_fma_f32 v[6:7], v[8:9], v[6:7], v[80:81]
	v_readlane_b32 s1, v252, 26
	v_cvt_pk_bf16_f32 v4, v4, v5
	v_cvt_pk_bf16_f32 v5, v6, v7
	s_or_b64 s[10:11], vcc, s[10:11]
	v_lshl_add_u64 v[24:25], v[24:25], 0, s[0:1]
	global_store_dwordx2 v[10:11], v[4:5], off offset:-2560
	s_andn2_b64 exec, exec, s[10:11]
	s_cbranch_execz .LBB0_128

.LBB0_126:
	s_or_b64 exec, exec, s[12:13]
	v_ashrrev_i32_e32 v35, 31, v34
	v_lshlrev_b64 v[8:9], v8, v[34:35]
	v_lshlrev_b64 v[4:5], 10, v[4:5]
	v_lshl_add_u64 v[4:5], v[4:5], 0, v[8:9]
	v_lshlrev_b64 v[4:5], 2, v[4:5]
	v_lshl_add_u64 v[32:33], v[10:11], 0, v[4:5]
	v_lshl_add_u64 v[4:5], v[6:7], 0, v[4:5]
	v_cndmask_b32_e64 v5, v33, v5, s[4:5]
	v_cndmask_b32_e64 v4, v32, v4, s[4:5]
	v_lshl_add_u64 v[4:5], v[4:5], 0, v[2:3]
	global_load_dwordx4 v[16:19], v[4:5], off
	global_load_dwordx4 v[12:15], v[4:5], off offset:1024
	global_load_dwordx4 v[8:11], v[4:5], off offset:2048
	s_nop 0
	global_load_dwordx4 v[4:7], v[4:5], off offset:3072
	v_readlane_b32 s12, v253, 48
	v_readlane_b32 s54, v252, 34
	v_readlane_b32 s60, v252, 36
	v_readlane_b32 s64, v252, 38
	s_andn2_b64 vcc, exec, s[8:9]
	v_cndmask_b32_e64 v1, v34, 8, s[0:1]
	v_readlane_b32 s13, v253, 49
	v_readlane_b32 s55, v252, 35
	v_readlane_b32 s61, v252, 37
	v_readlane_b32 s65, v252, 39
	s_mov_b32 s52, 0x78787879
	s_movk_i32 s53, 0xff
	s_cbranch_vccnz .LBB0_121
	global_load_dwordx2 v[34:35], v[24:25], off
	global_load_dwordx2 v[70:71], v[24:25], off offset:512
	global_load_dwordx2 v[72:73], v[24:25], off offset:1024
	global_load_dwordx2 v[74:75], v[24:25], off offset:1536
	v_add_u32_e32 v38, v1, v36
	v_mul_lo_u32 v54, v38, s17
	v_ashrrev_i32_e32 v55, 31, v54
	v_lshl_add_u64 v[54:55], v[54:55], 2, s[12:13]
	v_lshl_add_u64 v[54:55], v[54:55], 0, v[2:3]
	s_mov_b64 s[0:1], 0x2000
	s_waitcnt vmcnt(17)
	v_lshl_add_u64 v[62:63], v[54:55], 0, s[0:1]
	s_movk_i32 s0, 0x2000
	v_mov_b32_e32 v27, v222
	v_mov_b32_e32 v29, v222
	v_mov_b32_e32 v31, v222
	v_mov_b32_e32 v37, v222
	v_mov_b32_e32 v100, v222
	v_mov_b32_e32 v101, v222
	s_waitcnt vmcnt(16)
	v_add_co_u32_e32 v66, vcc, s0, v54
	global_load_dwordx4 v[38:41], v[20:21], off
	global_load_dwordx4 v[42:45], v[20:21], off offset:1024
	global_load_dwordx4 v[46:49], v[20:21], off offset:2048
	global_load_dwordx4 v[50:53], v[20:21], off offset:3072
	v_addc_co_u32_e32 v67, vcc, 0, v55, vcc
	global_load_dwordx4 v[54:57], v[62:63], off offset:1024
	global_load_dwordx4 v[58:61], v[62:63], off offset:2048
	s_nop 0
	global_load_dwordx4 v[62:65], v[62:63], off offset:3072
	s_nop 0
	global_load_dwordx4 v[66:69], v[66:67], off
	v_lshlrev_b32_e32 v27, 2, v27
	v_bitop3_b32 v27, v27, s18, v229 bitop3:0x6c
	v_lshlrev_b32_e32 v29, 2, v29
	v_bitop3_b32 v29, v29, 64, v229 bitop3:0x6c
	v_lshlrev_b32_e32 v31, 2, v31
	v_bitop3_b32 v31, v31, 32, v229 bitop3:0x6c
	v_lshl_add_u64 v[32:33], v[32:33], 0, v[2:3]
	s_waitcnt vmcnt(11)
	v_and_b32_e32 v77, 0xffff0000, v34
	s_waitcnt vmcnt(10)
	v_and_b32_e32 v79, 0xffff0000, v70
	v_lshlrev_b32_e32 v76, 16, v34
	v_lshlrev_b32_e32 v78, 16, v70
	s_waitcnt vmcnt(9)
	v_and_b32_e32 v81, 0xffff0000, v72
	s_waitcnt vmcnt(8)
	v_and_b32_e32 v83, 0xffff0000, v74
	v_mov_b32_e32 v86, v77
	v_mov_b32_e32 v87, v79
	v_lshlrev_b32_e32 v34, 16, v35
	v_lshlrev_b32_e32 v70, 16, v71
	v_lshlrev_b32_e32 v80, 16, v72
	v_lshlrev_b32_e32 v82, 16, v74
	v_mov_b32_e32 v84, v76
	v_mov_b32_e32 v85, v78
	v_mov_b32_e32 v94, v81
	v_mov_b32_e32 v95, v83
	v_pk_mul_f32 v[86:87], v[86:87], v[86:87]
	v_and_b32_e32 v35, 0xffff0000, v35
	v_and_b32_e32 v71, 0xffff0000, v71
	v_lshlrev_b32_e32 v72, 16, v73
	v_lshlrev_b32_e32 v74, 16, v75
	v_mov_b32_e32 v88, v34
	v_mov_b32_e32 v89, v70
	v_mov_b32_e32 v92, v80
	v_mov_b32_e32 v93, v82
	v_pk_mul_f32 v[94:95], v[94:95], v[94:95]
	v_pk_fma_f32 v[84:85], v[84:85], v[84:85], v[86:87]
	v_and_b32_e32 v73, 0xffff0000, v73
	v_and_b32_e32 v75, 0xffff0000, v75
	v_mov_b32_e32 v90, v35
	v_mov_b32_e32 v91, v71
	v_mov_b32_e32 v96, v72
	v_mov_b32_e32 v97, v74
	v_pk_fma_f32 v[86:87], v[92:93], v[92:93], v[94:95]
	v_pk_fma_f32 v[84:85], v[88:89], v[88:89], v[84:85]
	v_mov_b32_e32 v98, v73
	v_mov_b32_e32 v99, v75
	v_pk_fma_f32 v[86:87], v[96:97], v[96:97], v[86:87]
	v_pk_fma_f32 v[84:85], v[90:91], v[90:91], v[84:85]
	v_pk_fma_f32 v[86:87], v[98:99], v[98:99], v[86:87]
	v_add_f32_e32 v84, v84, v85
	v_add_f32_e32 v84, v84, v86
	v_add_f32_e32 v84, v84, v87
	s_waitcnt lgkmcnt(0)
	s_waitcnt lgkmcnt(0)
	v_lshlrev_b32_e32 v31, 2, v37
	v_bitop3_b32 v31, v31, 16, v229 bitop3:0x6c
	s_waitcnt lgkmcnt(0)
	v_lshlrev_b32_e32 v31, 2, v100
	v_bitop3_b32 v31, v31, 8, v229 bitop3:0x6c
	s_waitcnt lgkmcnt(0)
	v_lshlrev_b32_e32 v31, 2, v101
	v_bitop3_b32 v31, v31, 4, v229 bitop3:0x6c
	s_waitcnt lgkmcnt(0)
	s_waitcnt lgkmcnt(0)
	v_mov_b32_e32 v27, v84
	s_nop 1
	v_add_f32_dpp v27, v27, v27 quad_perm:[1,0,3,2] row_mask:0xf bank_mask:0xf
	s_nop 1
	v_add_f32_dpp v27, v27, v27 quad_perm:[2,3,0,1] row_mask:0xf bank_mask:0xf
	s_nop 1
	v_add_f32_dpp v27, v27, v27 row_half_mirror row_mask:0xf bank_mask:0xf
	s_nop 1
	v_add_f32_dpp v27, v27, v27 row_mirror row_mask:0xf bank_mask:0xf
	s_nop 1
	v_add_f32_dpp v27, v27, v27 row_bcast:15 row_mask:0xa bank_mask:0xf
	s_nop 1
	v_add_f32_dpp v27, v27, v27 row_bcast:31 row_mask:0xc bank_mask:0xf
	s_nop 1
	v_readlane_b32 s98, v27, 63
	s_nop 1
	v_mov_b32_e32 v27, s98
	v_fmamk_f32 v27, v27, 0x3a800000, v223
	v_mul_f32_e32 v29, 0x4b800000, v27
	v_cmp_gt_f32_e32 vcc, s19, v27
	s_nop 1
	v_cndmask_b32_e32 v27, v27, v29, vcc
	v_rsq_f32_e32 v27, v27
	s_nop 0
	v_mul_f32_e32 v29, 0x45800000, v27
	v_cndmask_b32_e32 v84, v27, v29, vcc
	v_pk_mul_f32 v[76:77], v[84:85], v[76:77] op_sel_hi:[0,1]
	v_pk_mul_f32 v[34:35], v[84:85], v[34:35] op_sel_hi:[0,1]
	v_pk_mul_f32 v[78:79], v[84:85], v[78:79] op_sel_hi:[0,1]
	v_pk_mul_f32 v[70:71], v[84:85], v[70:71] op_sel_hi:[0,1]
	v_pk_mul_f32 v[80:81], v[84:85], v[80:81] op_sel_hi:[0,1]
	v_pk_mul_f32 v[72:73], v[84:85], v[72:73] op_sel_hi:[0,1]
	v_pk_mul_f32 v[82:83], v[84:85], v[82:83] op_sel_hi:[0,1]
	v_pk_mul_f32 v[74:75], v[84:85], v[74:75] op_sel_hi:[0,1]
	s_waitcnt vmcnt(7)
	v_pk_mul_f32 v[38:39], v[38:39], v[76:77]
	v_pk_mul_f32 v[34:35], v[40:41], v[34:35]
	s_waitcnt vmcnt(6)
	v_pk_mul_f32 v[40:41], v[78:79], v[42:43]
	v_pk_mul_f32 v[42:43], v[70:71], v[44:45]
	s_waitcnt vmcnt(5)
	v_pk_mul_f32 v[44:45], v[80:81], v[46:47]
	v_pk_mul_f32 v[46:47], v[72:73], v[48:49]
	s_waitcnt vmcnt(4)
	v_pk_mul_f32 v[48:49], v[82:83], v[50:51]
	v_pk_mul_f32 v[50:51], v[74:75], v[52:53]
	s_waitcnt vmcnt(0)
	v_pk_fma_f32 v[16:17], v[66:67], v[38:39], v[16:17]
	v_pk_fma_f32 v[18:19], v[68:69], v[34:35], v[18:19]
	v_pk_fma_f32 v[12:13], v[54:55], v[40:41], v[12:13]
	v_pk_fma_f32 v[14:15], v[56:57], v[42:43], v[14:15]
	v_pk_fma_f32 v[8:9], v[58:59], v[44:45], v[8:9]
	v_pk_fma_f32 v[10:11], v[60:61], v[46:47], v[10:11]
	v_pk_fma_f32 v[4:5], v[62:63], v[48:49], v[4:5]
	v_pk_fma_f32 v[6:7], v[64:65], v[50:51], v[6:7]
	global_store_dwordx4 v[32:33], v[16:19], off
	global_store_dwordx4 v[32:33], v[12:15], off offset:1024
	global_store_dwordx4 v[32:33], v[8:11], off offset:2048
	global_store_dwordx4 v[32:33], v[4:7], off offset:3072
	s_branch .LBB0_121

.LBB0_1175:
	v_mul_hi_i32 v2, v0, s6
	v_lshrrev_b32_e32 v9, 31, v2
	v_ashrrev_i32_e32 v2, 11, v2
	v_add_u32_e32 v10, v2, v9
	v_mad_i32_i24 v2, v10, s7, v0
	v_cmp_lt_i32_e32 vcc, s8, v2
	s_and_saveexec_b64 s[4:5], vcc
	s_cbranch_execz .LBB0_1174
	global_load_dwordx2 v[62:63], v[6:7], off
	global_load_dwordx2 v[64:65], v[6:7], off offset:512
	global_load_dwordx2 v[66:67], v[6:7], off offset:1024
	global_load_dwordx2 v[68:69], v[6:7], off offset:1536
	v_add_u32_e32 v2, 0xffffff00, v2
	v_mul_i32_i24_e32 v14, 0xc00, v10
	v_ashrrev_i32_e32 v11, 31, v10
	v_lshlrev_b64 v[16:17], 12, v[2:3]
	v_ashrrev_i32_e32 v15, 31, v14
	v_mov_b32_e32 v9, v3
	v_lshlrev_b64 v[10:11], 24, v[10:11]
	v_lshl_add_u64 v[16:17], s[28:29], 0, v[16:17]
	v_lshl_add_u64 v[14:15], v[14:15], 2, s[30:31]
	v_lshl_add_u64 v[10:11], v[16:17], 0, v[10:11]
	v_lshl_add_u64 v[14:15], v[14:15], 0, v[8:9]
	v_mov_b32_e32 v13, v222
	s_waitcnt vmcnt(15)
	v_mov_b32_e32 v94, v222
	v_mov_b32_e32 v95, v222
	s_waitcnt vmcnt(14)
	v_mov_b32_e32 v96, v222
	v_mov_b32_e32 v97, v222
	v_mov_b32_e32 v98, v222
	v_lshl_add_u64 v[10:11], v[10:11], 0, v[8:9]
	v_add_co_u32_e32 v72, vcc, s11, v14
	v_lshl_add_u64 v[70:71], v[14:15], 0, s[2:3]
	s_nop 0
	v_addc_co_u32_e32 v73, vcc, 0, v15, vcc
	global_load_dwordx4 v[14:17], v[10:11], off
	global_load_dwordx4 v[18:21], v[10:11], off offset:1024
	global_load_dwordx4 v[22:25], v[10:11], off offset:2048
	global_load_dwordx4 v[26:29], v[10:11], off offset:3072
	global_load_dwordx4 v[30:33], v[4:5], off
	global_load_dwordx4 v[34:37], v[4:5], off offset:1024
	global_load_dwordx4 v[38:41], v[70:71], off offset:1024
	global_load_dwordx4 v[42:45], v[70:71], off offset:2048
	global_load_dwordx4 v[46:49], v[72:73], off
	global_load_dwordx4 v[50:53], v[70:71], off offset:3072
	global_load_dwordx4 v[54:57], v[4:5], off offset:2048
	global_load_dwordx4 v[58:61], v[4:5], off offset:3072
	v_lshlrev_b32_e32 v2, 2, v13
	v_bitop3_b32 v2, v2, s9, v12 bitop3:0x6c
	v_lshlrev_b32_e32 v13, 2, v94
	v_bitop3_b32 v13, v13, 64, v12 bitop3:0x6c
	s_waitcnt vmcnt(15)
	v_and_b32_e32 v71, 0xffff0000, v62
	s_waitcnt vmcnt(14)
	v_and_b32_e32 v73, 0xffff0000, v64
	v_lshlrev_b32_e32 v70, 16, v62
	v_lshlrev_b32_e32 v72, 16, v64
	s_waitcnt vmcnt(13)
	v_and_b32_e32 v75, 0xffff0000, v66
	s_waitcnt vmcnt(12)
	v_and_b32_e32 v77, 0xffff0000, v68
	v_mov_b32_e32 v80, v71
	v_mov_b32_e32 v81, v73
	v_lshlrev_b32_e32 v62, 16, v63
	v_lshlrev_b32_e32 v64, 16, v65
	v_lshlrev_b32_e32 v74, 16, v66
	v_lshlrev_b32_e32 v76, 16, v68
	v_mov_b32_e32 v78, v70
	v_mov_b32_e32 v79, v72
	v_mov_b32_e32 v88, v75
	v_mov_b32_e32 v89, v77
	v_pk_mul_f32 v[80:81], v[80:81], v[80:81]
	v_and_b32_e32 v63, 0xffff0000, v63
	v_and_b32_e32 v65, 0xffff0000, v65
	v_lshlrev_b32_e32 v66, 16, v67
	v_lshlrev_b32_e32 v68, 16, v69
	v_mov_b32_e32 v82, v62
	v_mov_b32_e32 v83, v64
	v_mov_b32_e32 v86, v74
	v_mov_b32_e32 v87, v76
	v_pk_mul_f32 v[88:89], v[88:89], v[88:89]
	v_pk_fma_f32 v[78:79], v[78:79], v[78:79], v[80:81]
	v_and_b32_e32 v67, 0xffff0000, v67
	v_and_b32_e32 v69, 0xffff0000, v69
	v_mov_b32_e32 v84, v63
	v_mov_b32_e32 v85, v65
	v_mov_b32_e32 v90, v66
	v_mov_b32_e32 v91, v68
	v_pk_fma_f32 v[80:81], v[86:87], v[86:87], v[88:89]
	v_pk_fma_f32 v[78:79], v[82:83], v[82:83], v[78:79]
	v_mov_b32_e32 v92, v67
	v_mov_b32_e32 v93, v69
	v_pk_fma_f32 v[80:81], v[90:91], v[90:91], v[80:81]
	v_pk_fma_f32 v[78:79], v[84:85], v[84:85], v[78:79]
	v_pk_fma_f32 v[80:81], v[92:93], v[92:93], v[80:81]
	v_add_f32_e32 v9, v78, v79
	v_add_f32_e32 v9, v9, v80
	v_add_f32_e32 v9, v9, v81
	s_waitcnt lgkmcnt(0)
	v_lshlrev_b32_e32 v13, 2, v95
	v_bitop3_b32 v13, v13, 32, v12 bitop3:0x6c
	s_waitcnt lgkmcnt(0)
	v_lshlrev_b32_e32 v13, 2, v96
	v_bitop3_b32 v13, v13, 16, v12 bitop3:0x6c
	s_waitcnt lgkmcnt(0)
	v_lshlrev_b32_e32 v13, 2, v97
	v_bitop3_b32 v13, v13, 8, v12 bitop3:0x6c
	s_waitcnt lgkmcnt(0)
	v_lshlrev_b32_e32 v13, 2, v98
	v_bitop3_b32 v13, v13, 4, v12 bitop3:0x6c
	s_waitcnt lgkmcnt(0)
	s_waitcnt lgkmcnt(0)
	v_mov_b32_e32 v2, v9
	s_nop 1
	v_add_f32_dpp v2, v2, v2 quad_perm:[1,0,3,2] row_mask:0xf bank_mask:0xf
	s_nop 1
	v_add_f32_dpp v2, v2, v2 quad_perm:[2,3,0,1] row_mask:0xf bank_mask:0xf
	s_nop 1
	v_add_f32_dpp v2, v2, v2 row_half_mirror row_mask:0xf bank_mask:0xf
	s_nop 1
	v_add_f32_dpp v2, v2, v2 row_mirror row_mask:0xf bank_mask:0xf
	s_nop 1
	v_add_f32_dpp v2, v2, v2 row_bcast:15 row_mask:0xa bank_mask:0xf
	s_nop 1
	v_add_f32_dpp v2, v2, v2 row_bcast:31 row_mask:0xc bank_mask:0xf
	s_nop 1
	v_readlane_b32 s98, v2, 63
	s_nop 1
	v_mov_b32_e32 v2, s98
	v_fmamk_f32 v2, v2, 0x3a800000, v1
	v_mul_f32_e32 v9, 0x4b800000, v2
	v_cmp_gt_f32_e32 vcc, s10, v2
	s_nop 1
	v_cndmask_b32_e32 v2, v2, v9, vcc
	v_rsq_f32_e32 v2, v2
	s_nop 0
	v_mul_f32_e32 v9, 0x45800000, v2
	v_cndmask_b32_e32 v2, v2, v9, vcc
	v_pk_mul_f32 v[70:71], v[2:3], v[70:71] op_sel_hi:[0,1]
	v_pk_mul_f32 v[62:63], v[2:3], v[62:63] op_sel_hi:[0,1]
	v_pk_mul_f32 v[72:73], v[2:3], v[72:73] op_sel_hi:[0,1]
	v_pk_mul_f32 v[64:65], v[2:3], v[64:65] op_sel_hi:[0,1]
	s_waitcnt vmcnt(7)
	v_pk_mul_f32 v[30:31], v[30:31], v[70:71]
	v_pk_mul_f32 v[32:33], v[32:33], v[62:63]
	s_waitcnt vmcnt(6)
	v_pk_mul_f32 v[34:35], v[72:73], v[34:35]
	v_pk_mul_f32 v[36:37], v[64:65], v[36:37]
	s_waitcnt vmcnt(3)
	v_pk_fma_f32 v[14:15], v[46:47], v[30:31], v[14:15]
	v_pk_fma_f32 v[16:17], v[48:49], v[32:33], v[16:17]
	v_pk_mul_f32 v[74:75], v[2:3], v[74:75] op_sel_hi:[0,1]
	v_pk_mul_f32 v[66:67], v[2:3], v[66:67] op_sel_hi:[0,1]
	v_pk_fma_f32 v[18:19], v[38:39], v[34:35], v[18:19]
	v_pk_fma_f32 v[20:21], v[40:41], v[36:37], v[20:21]
	global_store_dwordx4 v[10:11], v[14:17], off
	global_store_dwordx4 v[10:11], v[18:21], off offset:1024
	s_waitcnt vmcnt(3)
	v_pk_mul_f32 v[54:55], v[74:75], v[54:55]
	v_pk_mul_f32 v[14:15], v[2:3], v[76:77] op_sel_hi:[0,1]
	v_pk_mul_f32 v[16:17], v[2:3], v[68:69] op_sel_hi:[0,1]
	v_pk_mul_f32 v[56:57], v[66:67], v[56:57]
	s_waitcnt vmcnt(2)
	v_pk_mul_f32 v[14:15], v[14:15], v[58:59]
	v_pk_mul_f32 v[16:17], v[16:17], v[60:61]
	v_pk_fma_f32 v[22:23], v[42:43], v[54:55], v[22:23]
	v_pk_fma_f32 v[24:25], v[44:45], v[56:57], v[24:25]
	v_pk_fma_f32 v[14:15], v[50:51], v[14:15], v[26:27]
	v_pk_fma_f32 v[16:17], v[52:53], v[16:17], v[28:29]
	global_store_dwordx4 v[10:11], v[22:25], off offset:2048
	global_store_dwordx4 v[10:11], v[14:17], off offset:3072
	s_branch .LBB0_1174
